# stack + FFN-down fused epilogue: 4 gate-vector loads in one round
# baseline (speedup 1.0000x reference)
.LBB0_333:
	v_readlane_b32 s6, v253, 9
	v_readlane_b32 s7, v253, 10
	s_lshl_b64 s[6:7], s[6:7], 2
	s_add_u32 s2, s18, s6
	s_addc_u32 s6, s19, s7
	s_add_u32 s62, s2, 0x100000
	s_addc_u32 s63, s6, 0
	s_lshl_b32 s2, s50, 2
	s_add_u32 s2, s62, s2
	s_addc_u32 s12, s63, 0
	s_lshl_b64 s[6:7], s[66:67], 2
	s_add_u32 s8, s8, s6
	s_addc_u32 s9, s9, s7
	s_add_u32 s6, s10, s6
	s_addc_u32 s7, s11, s7
	s_lshl_b32 s24, s82, 8
	s_waitcnt vmcnt(0)
	s_barrier
	v_mbcnt_lo_u32_b32 v0, -1, 0
	v_mbcnt_hi_u32_b32 v0, -1, v0
	s_lshl_b32 s11, s22, 8
	v_ashrrev_i32_e32 v130, 2, v0
	s_ashr_i32 s25, s24, 31
	s_ashr_i32 s10, s82, 3
	s_or_b32 s11, s11, s43
	v_and_b32_e32 v130, -4, v130
	s_lshl_b64 s[26:27], s[24:25], 11
	v_add_u32_e32 v180, s11, v130
	s_add_u32 s14, s28, s26
	v_and_or_b32 v196, v0, 15, s17
	s_addc_u32 s15, s29, s27
	v_ashrrev_i32_e32 v181, 31, v180
	v_ashrrev_i32_e32 v197, 31, v196
	v_or_b32_e32 v194, 16, v196
	v_lshl_add_u64 v[138:139], v[180:181], 1, s[14:15]
	v_lshlrev_b64 v[130:131], 11, v[196:197]
	v_ashrrev_i32_e32 v195, 31, v194
	v_or_b32_e32 v192, 32, v196
	v_add_u32_e32 v184, 0xa0, v196
	v_add_u32_e32 v188, 0x80, v196
	v_lshl_add_u64 v[142:143], v[138:139], 0, v[130:131]
	v_lshlrev_b64 v[130:131], 11, v[194:195]
	v_ashrrev_i32_e32 v193, 31, v192
	v_or_b32_e32 v190, 48, v196
	v_add_u32_e32 v186, 0x90, v196
	v_ashrrev_i32_e32 v185, 31, v184
	v_add_u32_e32 v182, 0xb0, v196
	s_mul_hi_i32 s11, s10, 0x2400
	s_mulk_i32 s10, 0x2400
	v_ashrrev_i32_e32 v189, 31, v188
	v_lshl_add_u64 v[144:145], v[138:139], 0, v[130:131]
	v_lshlrev_b64 v[130:131], 11, v[192:193]
	v_ashrrev_i32_e32 v191, 31, v190
	v_ashrrev_i32_e32 v187, 31, v186
	v_lshlrev_b64 v[152:153], 11, v[184:185]
	v_ashrrev_i32_e32 v183, 31, v182
	v_lshlrev_b64 v[140:141], 11, v[188:189]
	v_lshl_add_u64 v[146:147], v[138:139], 0, v[130:131]
	v_lshlrev_b64 v[130:131], 11, v[190:191]
	v_lshlrev_b64 v[150:151], 11, v[186:187]
	v_lshl_add_u64 v[162:163], v[138:139], 0, v[152:153]
	v_lshlrev_b64 v[152:153], 11, v[182:183]
	s_lshl_b64 s[28:29], s[10:11], 2
	v_lshl_add_u64 v[148:149], v[138:139], 0, v[130:131]
	v_lshl_add_u64 v[140:141], v[138:139], 0, v[140:141]
	v_lshl_add_u64 v[150:151], v[138:139], 0, v[150:151]
	v_lshl_add_u64 v[138:139], v[138:139], 0, v[152:153]
	s_add_u32 s10, s2, s28
	global_load_dwordx2 v[136:137], v[142:143], off
	global_load_dwordx2 v[134:135], v[144:145], off
	global_load_dwordx2 v[132:133], v[146:147], off
	global_load_dwordx2 v[224:225], v[140:141], off
	global_load_dwordx2 v[130:131], v[148:149], off
	global_load_dwordx2 v[222:223], v[150:151], off
	global_load_dwordx2 v[220:221], v[162:163], off
	global_load_dwordx2 v[218:219], v[138:139], off
	global_load_dwordx2 v[216:217], v[142:143], off offset:32
	global_load_dwordx2 v[214:215], v[144:145], off offset:32
	global_load_dwordx2 v[212:213], v[146:147], off offset:32
	global_load_dwordx2 v[210:211], v[148:149], off offset:32
	global_load_dwordx2 v[208:209], v[140:141], off offset:32
	global_load_dwordx2 v[206:207], v[150:151], off offset:32
	global_load_dwordx2 v[204:205], v[162:163], off offset:32
	global_load_dwordx2 v[202:203], v[138:139], off offset:32
	global_load_dwordx2 v[200:201], v[142:143], off offset:256
	global_load_dwordx2 v[176:177], v[144:145], off offset:256
	global_load_dwordx2 v[174:175], v[146:147], off offset:256
	global_load_dwordx2 v[172:173], v[148:149], off offset:256
	global_load_dwordx2 v[170:171], v[140:141], off offset:256
	global_load_dwordx2 v[168:169], v[150:151], off offset:256
	global_load_dwordx2 v[166:167], v[162:163], off offset:256
	global_load_dwordx2 v[164:165], v[138:139], off offset:256
	global_load_dwordx2 v[160:161], v[142:143], off offset:288
	global_load_dwordx2 v[158:159], v[144:145], off offset:288
	global_load_dwordx2 v[156:157], v[146:147], off offset:288
	global_load_dwordx2 v[154:155], v[148:149], off offset:288
	global_load_dwordx2 v[152:153], v[140:141], off offset:288
	s_nop 0
	global_load_dwordx2 v[150:151], v[150:151], off offset:288
	s_nop 0
	global_load_dwordx2 v[148:149], v[162:163], off offset:288
	global_load_dwordx2 v[146:147], v[138:139], off offset:288
	s_addc_u32 s11, s12, s29
	v_lshlrev_b64 v[162:163], 2, v[180:181]
	v_lshl_add_u64 v[198:199], s[10:11], 0, v[162:163]
	global_load_dwordx4 v[138:141], v[198:199], off
	global_load_dwordx4 v[232:235], v[198:199], off offset:64
	global_load_dwordx4 v[236:239], v[198:199], off offset:512
	global_load_dwordx4 v[240:243], v[198:199], off offset:576
	s_waitcnt vmcnt(0)
	s_lshl_b32 s2, s53, 3
	s_mov_b32 s42, s50
	s_add_i32 s2, s2, 0
	v_pk_mul_f32 v[228:229], v[140:141], 0.5 op_sel_hi:[1, 0]
	v_pk_mul_f32 v[226:227], v[138:139], 0.5 op_sel_hi:[1, 0]
	v_cvt_f32_f16_e32 v138, v137
	v_cvt_f32_f16_sdwa v139, v137 dst_sel:DWORD dst_unused:UNUSED_PAD src0_sel:WORD_1
	v_cvt_f32_f16_e32 v140, v136
	v_cvt_f32_f16_sdwa v141, v136 dst_sel:DWORD dst_unused:UNUSED_PAD src0_sel:WORD_1
	v_pk_mul_f32 v[138:139], v[138:139], s[90:91] op_sel_hi:[1, 0]
	s_nop 0
	v_pk_fma_f32 v[144:145], v[128:129], v[228:229], v[138:139]
	v_pk_mul_f32 v[136:137], v[140:141], s[90:91] op_sel_hi:[1, 0]
	v_cvt_f32_f16_e32 v128, v134
	v_pk_fma_f32 v[142:143], v[126:127], v[226:227], v[136:137]
	v_cvt_f32_f16_e32 v126, v135
	v_cvt_f32_f16_sdwa v127, v135 dst_sel:DWORD dst_unused:UNUSED_PAD src0_sel:WORD_1
	v_cvt_f32_f16_sdwa v129, v134 dst_sel:DWORD dst_unused:UNUSED_PAD src0_sel:WORD_1
	v_pk_mul_f32 v[126:127], v[126:127], s[90:91] op_sel_hi:[1, 0]
	v_pk_mul_f32 v[128:129], v[128:129], s[90:91] op_sel_hi:[1, 0]
	v_pk_fma_f32 v[140:141], v[124:125], v[228:229], v[126:127]
	v_pk_fma_f32 v[138:139], v[122:123], v[226:227], v[128:129]
	v_cvt_f32_f16_e32 v122, v133
	v_cvt_f32_f16_sdwa v123, v133 dst_sel:DWORD dst_unused:UNUSED_PAD src0_sel:WORD_1
	v_cvt_f32_f16_e32 v124, v132
	v_cvt_f32_f16_sdwa v125, v132 dst_sel:DWORD dst_unused:UNUSED_PAD src0_sel:WORD_1
	v_pk_mul_f32 v[122:123], v[122:123], s[90:91] op_sel_hi:[1, 0]
	v_pk_mul_f32 v[124:125], v[124:125], s[90:91] op_sel_hi:[1, 0]
	v_pk_fma_f32 v[136:137], v[120:121], v[228:229], v[122:123]
	v_pk_fma_f32 v[134:135], v[118:119], v[226:227], v[124:125]
	v_cvt_f32_f16_e32 v118, v131
	v_cvt_f32_f16_sdwa v119, v131 dst_sel:DWORD dst_unused:UNUSED_PAD src0_sel:WORD_1
	v_cvt_f32_f16_e32 v120, v130
	v_cvt_f32_f16_sdwa v121, v130 dst_sel:DWORD dst_unused:UNUSED_PAD src0_sel:WORD_1
	v_pk_mul_f32 v[118:119], v[118:119], s[90:91] op_sel_hi:[1, 0]
	v_pk_mul_f32 v[120:121], v[120:121], s[90:91] op_sel_hi:[1, 0]
	v_pk_fma_f32 v[132:133], v[116:117], v[228:229], v[118:119]
	v_pk_fma_f32 v[130:131], v[114:115], v[226:227], v[120:121]
	v_cvt_f32_f16_e32 v114, v225
	v_cvt_f32_f16_sdwa v115, v225 dst_sel:DWORD dst_unused:UNUSED_PAD src0_sel:WORD_1
	v_cvt_f32_f16_e32 v116, v224
	v_cvt_f32_f16_sdwa v117, v224 dst_sel:DWORD dst_unused:UNUSED_PAD src0_sel:WORD_1
	v_pk_mul_f32 v[114:115], v[114:115], s[90:91] op_sel_hi:[1, 0]
	v_pk_mul_f32 v[116:117], v[116:117], s[90:91] op_sel_hi:[1, 0]
	v_pk_fma_f32 v[128:129], v[112:113], v[228:229], v[114:115]
	v_pk_fma_f32 v[126:127], v[110:111], v[226:227], v[116:117]
	v_cvt_f32_f16_e32 v110, v223
	v_cvt_f32_f16_sdwa v111, v223 dst_sel:DWORD dst_unused:UNUSED_PAD src0_sel:WORD_1
	v_cvt_f32_f16_e32 v112, v222
	v_cvt_f32_f16_sdwa v113, v222 dst_sel:DWORD dst_unused:UNUSED_PAD src0_sel:WORD_1
	v_pk_mul_f32 v[110:111], v[110:111], s[90:91] op_sel_hi:[1, 0]
	v_pk_mul_f32 v[112:113], v[112:113], s[90:91] op_sel_hi:[1, 0]
	v_pk_fma_f32 v[124:125], v[104:105], v[228:229], v[110:111]
	v_pk_fma_f32 v[122:123], v[102:103], v[226:227], v[112:113]
	v_cvt_f32_f16_e32 v102, v221
	v_cvt_f32_f16_sdwa v103, v221 dst_sel:DWORD dst_unused:UNUSED_PAD src0_sel:WORD_1
	v_cvt_f32_f16_e32 v104, v220
	v_cvt_f32_f16_sdwa v105, v220 dst_sel:DWORD dst_unused:UNUSED_PAD src0_sel:WORD_1
	v_pk_mul_f32 v[102:103], v[102:103], s[90:91] op_sel_hi:[1, 0]
	v_pk_mul_f32 v[104:105], v[104:105], s[90:91] op_sel_hi:[1, 0]
	v_pk_fma_f32 v[120:121], v[96:97], v[228:229], v[102:103]
	v_pk_fma_f32 v[118:119], v[94:95], v[226:227], v[104:105]
	v_cvt_f32_f16_e32 v94, v219
	v_cvt_f32_f16_sdwa v95, v219 dst_sel:DWORD dst_unused:UNUSED_PAD src0_sel:WORD_1
	v_cvt_f32_f16_e32 v96, v218
	v_cvt_f32_f16_sdwa v97, v218 dst_sel:DWORD dst_unused:UNUSED_PAD src0_sel:WORD_1
	v_pk_mul_f32 v[94:95], v[94:95], s[90:91] op_sel_hi:[1, 0]
	v_pk_mul_f32 v[96:97], v[96:97], s[90:91] op_sel_hi:[1, 0]
	v_pk_fma_f32 v[116:117], v[76:77], v[228:229], v[94:95]
	v_pk_fma_f32 v[114:115], v[74:75], v[226:227], v[96:97]
	v_cvt_f32_f16_e32 v94, v216
	v_cvt_f32_f16_sdwa v95, v216 dst_sel:DWORD dst_unused:UNUSED_PAD src0_sel:WORD_1
	v_cvt_f32_f16_e32 v96, v217
	v_cvt_f32_f16_sdwa v97, v217 dst_sel:DWORD dst_unused:UNUSED_PAD src0_sel:WORD_1
	v_pk_mul_f32 v[76:77], v[234:235], 0.5 op_sel_hi:[1, 0]
	v_pk_mul_f32 v[74:75], v[232:233], 0.5 op_sel_hi:[1, 0]
	v_pk_mul_f32 v[102:103], v[108:109], v[76:77]
	v_pk_mul_f32 v[104:105], v[106:107], v[74:75]
	v_pk_fma_f32 v[112:113], v[96:97], s[90:91], v[102:103] op_sel_hi:[1, 0, 1]
	v_pk_fma_f32 v[110:111], v[94:95], s[90:91], v[104:105] op_sel_hi:[1, 0, 1]
	v_cvt_f32_f16_e32 v94, v214
	v_cvt_f32_f16_sdwa v95, v214 dst_sel:DWORD dst_unused:UNUSED_PAD src0_sel:WORD_1
	v_cvt_f32_f16_e32 v96, v215
	v_cvt_f32_f16_sdwa v97, v215 dst_sel:DWORD dst_unused:UNUSED_PAD src0_sel:WORD_1
	v_pk_mul_f32 v[100:101], v[100:101], v[76:77]
	v_pk_mul_f32 v[98:99], v[98:99], v[74:75]
	v_pk_mul_f32 v[92:93], v[92:93], v[76:77]
	v_pk_fma_f32 v[108:109], v[96:97], s[90:91], v[100:101] op_sel_hi:[1, 0, 1]
	v_pk_fma_f32 v[106:107], v[94:95], s[90:91], v[98:99] op_sel_hi:[1, 0, 1]
	v_cvt_f32_f16_e32 v94, v212
	v_cvt_f32_f16_sdwa v95, v212 dst_sel:DWORD dst_unused:UNUSED_PAD src0_sel:WORD_1
	v_cvt_f32_f16_e32 v96, v213
	v_cvt_f32_f16_sdwa v97, v213 dst_sel:DWORD dst_unused:UNUSED_PAD src0_sel:WORD_1
	v_pk_mul_f32 v[90:91], v[90:91], v[74:75]
	v_pk_mul_f32 v[80:81], v[80:81], v[76:77]
	v_pk_fma_f32 v[102:103], v[94:95], s[90:91], v[90:91] op_sel_hi:[1, 0, 1]
	v_pk_fma_f32 v[104:105], v[96:97], s[90:91], v[92:93] op_sel_hi:[1, 0, 1]
	v_cvt_f32_f16_e32 v90, v210
	v_cvt_f32_f16_sdwa v91, v210 dst_sel:DWORD dst_unused:UNUSED_PAD src0_sel:WORD_1
	v_cvt_f32_f16_e32 v92, v211
	v_cvt_f32_f16_sdwa v93, v211 dst_sel:DWORD dst_unused:UNUSED_PAD src0_sel:WORD_1
	v_pk_mul_f32 v[78:79], v[78:79], v[74:75]
	v_pk_mul_f32 v[72:73], v[72:73], v[76:77]
	v_pk_fma_f32 v[98:99], v[90:91], s[90:91], v[78:79] op_sel_hi:[1, 0, 1]
	v_pk_fma_f32 v[100:101], v[92:93], s[90:91], v[80:81] op_sel_hi:[1, 0, 1]
	v_cvt_f32_f16_e32 v78, v208
	v_cvt_f32_f16_sdwa v79, v208 dst_sel:DWORD dst_unused:UNUSED_PAD src0_sel:WORD_1
	v_cvt_f32_f16_e32 v80, v209
	v_cvt_f32_f16_sdwa v81, v209 dst_sel:DWORD dst_unused:UNUSED_PAD src0_sel:WORD_1
	v_pk_mul_f32 v[70:71], v[70:71], v[74:75]
	v_pk_mul_f32 v[64:65], v[64:65], v[76:77]
	v_pk_fma_f32 v[94:95], v[78:79], s[90:91], v[70:71] op_sel_hi:[1, 0, 1]
	v_pk_fma_f32 v[96:97], v[80:81], s[90:91], v[72:73] op_sel_hi:[1, 0, 1]
	v_cvt_f32_f16_e32 v70, v206
	v_cvt_f32_f16_sdwa v71, v206 dst_sel:DWORD dst_unused:UNUSED_PAD src0_sel:WORD_1
	v_cvt_f32_f16_e32 v72, v207
	v_cvt_f32_f16_sdwa v73, v207 dst_sel:DWORD dst_unused:UNUSED_PAD src0_sel:WORD_1
	v_pk_mul_f32 v[62:63], v[62:63], v[74:75]
	v_pk_mul_f32 v[60:61], v[60:61], v[76:77]
	v_pk_fma_f32 v[90:91], v[70:71], s[90:91], v[62:63] op_sel_hi:[1, 0, 1]
	v_pk_fma_f32 v[92:93], v[72:73], s[90:91], v[64:65] op_sel_hi:[1, 0, 1]
	v_cvt_f32_f16_e32 v62, v204
	v_cvt_f32_f16_sdwa v63, v204 dst_sel:DWORD dst_unused:UNUSED_PAD src0_sel:WORD_1
	v_cvt_f32_f16_e32 v64, v205
	v_cvt_f32_f16_sdwa v65, v205 dst_sel:DWORD dst_unused:UNUSED_PAD src0_sel:WORD_1
	v_pk_mul_f32 v[58:59], v[58:59], v[74:75]
	v_pk_mul_f32 v[52:53], v[52:53], v[76:77]
	v_pk_fma_f32 v[78:79], v[62:63], s[90:91], v[58:59] op_sel_hi:[1, 0, 1]
	v_pk_fma_f32 v[80:81], v[64:65], s[90:91], v[60:61] op_sel_hi:[1, 0, 1]
	v_cvt_f32_f16_e32 v58, v202
	v_cvt_f32_f16_sdwa v59, v202 dst_sel:DWORD dst_unused:UNUSED_PAD src0_sel:WORD_1
	v_cvt_f32_f16_e32 v60, v203
	v_cvt_f32_f16_sdwa v61, v203 dst_sel:DWORD dst_unused:UNUSED_PAD src0_sel:WORD_1
	v_pk_mul_f32 v[50:51], v[50:51], v[74:75]
	v_pk_fma_f32 v[76:77], v[60:61], s[90:91], v[52:53] op_sel_hi:[1, 0, 1]
	v_pk_fma_f32 v[74:75], v[58:59], s[90:91], v[50:51] op_sel_hi:[1, 0, 1]
	s_nop 0
	v_pk_mul_f32 v[204:205], v[238:239], 0.5 op_sel_hi:[1, 0]
	v_pk_mul_f32 v[202:203], v[236:237], 0.5 op_sel_hi:[1, 0]
	v_cvt_f32_f16_e32 v50, v200
	v_cvt_f32_f16_sdwa v51, v200 dst_sel:DWORD dst_unused:UNUSED_PAD src0_sel:WORD_1
	v_cvt_f32_f16_e32 v52, v201
	v_cvt_f32_f16_sdwa v53, v201 dst_sel:DWORD dst_unused:UNUSED_PAD src0_sel:WORD_1
	v_pk_mul_f32 v[58:59], v[68:69], v[204:205]
	v_pk_mul_f32 v[60:61], v[66:67], v[202:203]
	v_pk_mul_f32 v[56:57], v[56:57], v[204:205]
	v_pk_fma_f32 v[72:73], v[52:53], s[90:91], v[58:59] op_sel_hi:[1, 0, 1]
	v_pk_fma_f32 v[70:71], v[50:51], s[90:91], v[60:61] op_sel_hi:[1, 0, 1]
	v_cvt_f32_f16_e32 v50, v176
	v_cvt_f32_f16_sdwa v51, v176 dst_sel:DWORD dst_unused:UNUSED_PAD src0_sel:WORD_1
	v_cvt_f32_f16_e32 v52, v177
	v_cvt_f32_f16_sdwa v53, v177 dst_sel:DWORD dst_unused:UNUSED_PAD src0_sel:WORD_1
	v_pk_mul_f32 v[54:55], v[54:55], v[202:203]
	v_pk_mul_f32 v[48:49], v[48:49], v[204:205]
	v_pk_fma_f32 v[66:67], v[50:51], s[90:91], v[54:55] op_sel_hi:[1, 0, 1]
	v_pk_fma_f32 v[68:69], v[52:53], s[90:91], v[56:57] op_sel_hi:[1, 0, 1]
	v_cvt_f32_f16_e32 v50, v174
	v_cvt_f32_f16_sdwa v51, v174 dst_sel:DWORD dst_unused:UNUSED_PAD src0_sel:WORD_1
	v_cvt_f32_f16_e32 v52, v175
	v_cvt_f32_f16_sdwa v53, v175 dst_sel:DWORD dst_unused:UNUSED_PAD src0_sel:WORD_1
	v_pk_mul_f32 v[46:47], v[46:47], v[202:203]
	v_pk_mul_f32 v[44:45], v[44:45], v[204:205]
	v_pk_fma_f32 v[62:63], v[50:51], s[90:91], v[46:47] op_sel_hi:[1, 0, 1]
	v_pk_fma_f32 v[64:65], v[52:53], s[90:91], v[48:49] op_sel_hi:[1, 0, 1]
	v_cvt_f32_f16_e32 v46, v172
	v_cvt_f32_f16_sdwa v47, v172 dst_sel:DWORD dst_unused:UNUSED_PAD src0_sel:WORD_1
	v_cvt_f32_f16_e32 v48, v173
	v_cvt_f32_f16_sdwa v49, v173 dst_sel:DWORD dst_unused:UNUSED_PAD src0_sel:WORD_1
	v_pk_mul_f32 v[42:43], v[42:43], v[202:203]
	v_pk_mul_f32 v[40:41], v[40:41], v[204:205]
	v_pk_fma_f32 v[58:59], v[46:47], s[90:91], v[42:43] op_sel_hi:[1, 0, 1]
	v_pk_fma_f32 v[60:61], v[48:49], s[90:91], v[44:45] op_sel_hi:[1, 0, 1]
	v_cvt_f32_f16_e32 v42, v170
	v_cvt_f32_f16_sdwa v43, v170 dst_sel:DWORD dst_unused:UNUSED_PAD src0_sel:WORD_1
	v_cvt_f32_f16_e32 v44, v171
	v_cvt_f32_f16_sdwa v45, v171 dst_sel:DWORD dst_unused:UNUSED_PAD src0_sel:WORD_1
	v_pk_mul_f32 v[38:39], v[38:39], v[202:203]
	v_pk_mul_f32 v[36:37], v[36:37], v[204:205]
	v_pk_fma_f32 v[54:55], v[42:43], s[90:91], v[38:39] op_sel_hi:[1, 0, 1]
	v_pk_fma_f32 v[56:57], v[44:45], s[90:91], v[40:41] op_sel_hi:[1, 0, 1]
	v_cvt_f32_f16_e32 v38, v168
	v_cvt_f32_f16_sdwa v39, v168 dst_sel:DWORD dst_unused:UNUSED_PAD src0_sel:WORD_1
	v_cvt_f32_f16_e32 v40, v169
	v_cvt_f32_f16_sdwa v41, v169 dst_sel:DWORD dst_unused:UNUSED_PAD src0_sel:WORD_1
	v_pk_mul_f32 v[34:35], v[34:35], v[202:203]
	v_pk_mul_f32 v[32:33], v[32:33], v[204:205]
	v_pk_fma_f32 v[50:51], v[38:39], s[90:91], v[34:35] op_sel_hi:[1, 0, 1]
	v_pk_fma_f32 v[52:53], v[40:41], s[90:91], v[36:37] op_sel_hi:[1, 0, 1]
	v_cvt_f32_f16_e32 v34, v166
	v_cvt_f32_f16_sdwa v35, v166 dst_sel:DWORD dst_unused:UNUSED_PAD src0_sel:WORD_1
	v_cvt_f32_f16_e32 v36, v167
	v_cvt_f32_f16_sdwa v37, v167 dst_sel:DWORD dst_unused:UNUSED_PAD src0_sel:WORD_1
	v_pk_mul_f32 v[30:31], v[30:31], v[202:203]
	v_pk_mul_f32 v[24:25], v[24:25], v[204:205]
	v_pk_fma_f32 v[46:47], v[34:35], s[90:91], v[30:31] op_sel_hi:[1, 0, 1]
	v_pk_fma_f32 v[48:49], v[36:37], s[90:91], v[32:33] op_sel_hi:[1, 0, 1]
	v_cvt_f32_f16_e32 v30, v164
	v_cvt_f32_f16_sdwa v31, v164 dst_sel:DWORD dst_unused:UNUSED_PAD src0_sel:WORD_1
	v_cvt_f32_f16_e32 v32, v165
	v_cvt_f32_f16_sdwa v33, v165 dst_sel:DWORD dst_unused:UNUSED_PAD src0_sel:WORD_1
	v_pk_mul_f32 v[22:23], v[22:23], v[202:203]
	v_pk_fma_f32 v[44:45], v[32:33], s[90:91], v[24:25] op_sel_hi:[1, 0, 1]
	v_pk_fma_f32 v[42:43], v[30:31], s[90:91], v[22:23] op_sel_hi:[1, 0, 1]
	s_nop 0
	v_mov_b32_e32 v168, v110
	v_mov_b32_e32 v169, v113
	v_add_f32_e32 v170, v72, v73
	v_pk_mul_f32 v[166:167], v[242:243], 0.5 op_sel_hi:[1, 0]
	v_pk_mul_f32 v[164:165], v[240:241], 0.5 op_sel_hi:[1, 0]
	v_cvt_f32_f16_e32 v22, v160
	v_cvt_f32_f16_sdwa v23, v160 dst_sel:DWORD dst_unused:UNUSED_PAD src0_sel:WORD_1
	v_cvt_f32_f16_e32 v24, v161
	v_cvt_f32_f16_sdwa v25, v161 dst_sel:DWORD dst_unused:UNUSED_PAD src0_sel:WORD_1
	v_pk_mul_f32 v[30:31], v[88:89], v[166:167]
	v_pk_mul_f32 v[32:33], v[86:87], v[164:165]
	v_pk_mul_f32 v[34:35], v[82:83], v[164:165]
	v_pk_fma_f32 v[40:41], v[24:25], s[90:91], v[30:31] op_sel_hi:[1, 0, 1]
	v_pk_fma_f32 v[38:39], v[22:23], s[90:91], v[32:33] op_sel_hi:[1, 0, 1]
	v_cvt_f32_f16_e32 v22, v158
	v_cvt_f32_f16_sdwa v23, v158 dst_sel:DWORD dst_unused:UNUSED_PAD src0_sel:WORD_1
	v_cvt_f32_f16_e32 v24, v159
	v_cvt_f32_f16_sdwa v25, v159 dst_sel:DWORD dst_unused:UNUSED_PAD src0_sel:WORD_1
	v_pk_mul_f32 v[30:31], v[84:85], v[166:167]
	v_pk_mul_f32 v[28:29], v[28:29], v[166:167]
	v_pk_mul_f32 v[26:27], v[26:27], v[164:165]
	v_pk_fma_f32 v[32:33], v[24:25], s[90:91], v[30:31] op_sel_hi:[1, 0, 1]
	v_pk_fma_f32 v[30:31], v[22:23], s[90:91], v[34:35] op_sel_hi:[1, 0, 1]
	v_cvt_f32_f16_e32 v22, v156
	v_cvt_f32_f16_sdwa v23, v156 dst_sel:DWORD dst_unused:UNUSED_PAD src0_sel:WORD_1
	v_cvt_f32_f16_e32 v24, v157
	v_cvt_f32_f16_sdwa v25, v157 dst_sel:DWORD dst_unused:UNUSED_PAD src0_sel:WORD_1
	v_pk_mul_f32 v[20:21], v[20:21], v[166:167]
	v_pk_fma_f32 v[34:35], v[22:23], s[90:91], v[26:27] op_sel_hi:[1, 0, 1]
	v_cvt_f32_f16_e32 v22, v154
	v_pk_fma_f32 v[36:37], v[24:25], s[90:91], v[28:29] op_sel_hi:[1, 0, 1]
	v_cvt_f32_f16_sdwa v23, v154 dst_sel:DWORD dst_unused:UNUSED_PAD src0_sel:WORD_1
	v_cvt_f32_f16_e32 v24, v155
	v_cvt_f32_f16_sdwa v25, v155 dst_sel:DWORD dst_unused:UNUSED_PAD src0_sel:WORD_1
	v_pk_mul_f32 v[18:19], v[18:19], v[164:165]
	v_pk_mul_f32 v[16:17], v[16:17], v[166:167]
	v_pk_fma_f32 v[26:27], v[22:23], s[90:91], v[18:19] op_sel_hi:[1, 0, 1]
	v_pk_fma_f32 v[28:29], v[24:25], s[90:91], v[20:21] op_sel_hi:[1, 0, 1]
	v_cvt_f32_f16_e32 v18, v152
	v_cvt_f32_f16_sdwa v19, v152 dst_sel:DWORD dst_unused:UNUSED_PAD src0_sel:WORD_1
	v_cvt_f32_f16_e32 v20, v153
	v_cvt_f32_f16_sdwa v21, v153 dst_sel:DWORD dst_unused:UNUSED_PAD src0_sel:WORD_1
	v_pk_mul_f32 v[14:15], v[14:15], v[164:165]
	v_pk_mul_f32 v[12:13], v[12:13], v[166:167]
	v_pk_fma_f32 v[22:23], v[18:19], s[90:91], v[14:15] op_sel_hi:[1, 0, 1]
	v_pk_fma_f32 v[24:25], v[20:21], s[90:91], v[16:17] op_sel_hi:[1, 0, 1]
	v_cvt_f32_f16_e32 v14, v150
	v_cvt_f32_f16_sdwa v15, v150 dst_sel:DWORD dst_unused:UNUSED_PAD src0_sel:WORD_1
	v_cvt_f32_f16_e32 v16, v151
	v_cvt_f32_f16_sdwa v17, v151 dst_sel:DWORD dst_unused:UNUSED_PAD src0_sel:WORD_1
	v_pk_mul_f32 v[10:11], v[10:11], v[164:165]
	v_pk_mul_f32 v[8:9], v[8:9], v[166:167]
	v_pk_fma_f32 v[18:19], v[14:15], s[90:91], v[10:11] op_sel_hi:[1, 0, 1]
	v_pk_fma_f32 v[20:21], v[16:17], s[90:91], v[12:13] op_sel_hi:[1, 0, 1]
	v_cvt_f32_f16_e32 v10, v148
	v_cvt_f32_f16_sdwa v11, v148 dst_sel:DWORD dst_unused:UNUSED_PAD src0_sel:WORD_1
	v_cvt_f32_f16_e32 v12, v149
	v_cvt_f32_f16_sdwa v13, v149 dst_sel:DWORD dst_unused:UNUSED_PAD src0_sel:WORD_1
	v_pk_mul_f32 v[6:7], v[6:7], v[164:165]
	v_pk_mul_f32 v[4:5], v[4:5], v[166:167]
	v_pk_fma_f32 v[14:15], v[10:11], s[90:91], v[6:7] op_sel_hi:[1, 0, 1]
	v_pk_fma_f32 v[16:17], v[12:13], s[90:91], v[8:9] op_sel_hi:[1, 0, 1]
	v_cvt_f32_f16_e32 v6, v146
	v_cvt_f32_f16_sdwa v7, v146 dst_sel:DWORD dst_unused:UNUSED_PAD src0_sel:WORD_1
	v_cvt_f32_f16_e32 v8, v147
	v_cvt_f32_f16_sdwa v9, v147 dst_sel:DWORD dst_unused:UNUSED_PAD src0_sel:WORD_1
	v_pk_mul_f32 v[2:3], v[2:3], v[164:165]
	v_pk_fma_f32 v[4:5], v[8:9], s[90:91], v[4:5] op_sel_hi:[1, 0, 1]
	v_pk_fma_f32 v[2:3], v[6:7], s[90:91], v[2:3] op_sel_hi:[1, 0, 1]
	s_nop 0
	v_lshl_add_u64 v[6:7], s[8:9], 0, v[162:163]
	v_lshl_add_u64 v[10:11], s[6:7], 0, v[162:163]
	global_load_dwordx4 v[158:161], v[6:7], off
	global_load_dwordx4 v[162:165], v[10:11], off
	global_load_dwordx4 v[146:149], v[6:7], off offset:64
	global_load_dwordx4 v[150:153], v[10:11], off offset:64
	global_load_dwordx4 v[82:85], v[6:7], off offset:512
	global_load_dwordx4 v[86:89], v[10:11], off offset:512
	s_nop 0
	global_load_dwordx4 v[6:9], v[6:7], off offset:576
	s_nop 0
	global_load_dwordx4 v[10:13], v[10:11], off offset:576
	v_and_b32_e32 v155, 64, v249
	v_xor_b32_e32 v154, 16, v249
	v_add_u32_e32 v155, 64, v155
	v_cmp_lt_i32_e32 vcc, v154, v155
	v_xor_b32_e32 v156, 32, v249
	v_mov_b32_e32 v157, v144
	v_cndmask_b32_e32 v154, v249, v154, vcc
	v_cmp_lt_i32_e32 vcc, v156, v155
	v_mov_b32_e32 v166, v142
	v_mov_b32_e32 v167, v145
	v_cndmask_b32_e32 v155, v249, v156, vcc
	v_mov_b32_e32 v156, v143
	v_pk_add_f32 v[156:157], v[156:157], v[166:167]
	v_mov_b32_e32 v166, v111
	v_mov_b32_e32 v167, v112
	v_pk_add_f32 v[166:167], v[166:167], v[168:169]
	v_add_f32_e32 v156, v156, v157
	v_pk_add_f32 v[166:167], v[166:167], v[166:167] op_sel:[0,1] op_sel_hi:[1,0]
	v_add_f32_e32 v156, 0, v156
	v_add_f32_e32 v168, v70, v71
	v_mov_b32_e32 v157, v38
	v_mov_b32_e32 v167, v39
	v_mov_b32_e32 v169, v40
	v_mov_b32_e32 v171, v41
	v_pk_add_f32 v[156:157], v[156:157], v[166:167]
	v_pk_add_f32 v[166:167], v[168:169], v[170:171]
	v_lshlrev_b32_e32 v154, 2, v154
	v_pk_add_f32 v[156:157], v[156:157], v[166:167]
	v_lshlrev_b32_e32 v155, 2, v155
	v_add_f32_e32 v156, v156, v157
	ds_bpermute_b32 v157, v154, v156
	v_cmp_gt_u32_e32 vcc, 16, v0
	s_waitcnt lgkmcnt(0)
	v_add_f32_e32 v156, v156, v157
	ds_bpermute_b32 v157, v155, v156
	s_waitcnt lgkmcnt(0)
	v_add_f32_e32 v156, v156, v157
	v_fmamk_f32 v166, v156, 0xbc800000, v145
	v_fmamk_f32 v168, v156, 0xbc800000, v143
	v_fmamk_f32 v157, v156, 0xbc800000, v144
	v_fmamk_f32 v167, v156, 0xbc800000, v142
	v_mul_f32_e32 v168, v168, v168
	v_mul_f32_e32 v166, v166, v166
	v_fmac_f32_e32 v168, v167, v167
	v_fmac_f32_e32 v166, v157, v157
	v_fmamk_f32 v167, v156, 0xbc800000, v113
	v_fmamk_f32 v169, v156, 0xbc800000, v111
	v_add_f32_e32 v157, v168, v166
	v_fmamk_f32 v166, v156, 0xbc800000, v112
	v_fmamk_f32 v168, v156, 0xbc800000, v110
	v_mul_f32_e32 v169, v169, v169
	v_mul_f32_e32 v167, v167, v167
	v_fmac_f32_e32 v169, v168, v168
	v_fmac_f32_e32 v167, v166, v166
	v_add_f32_e32 v166, v169, v167
	v_fmamk_f32 v167, v156, 0xbc800000, v73
	v_fmamk_f32 v169, v156, 0xbc800000, v71
	v_add_f32_e32 v157, v157, v166
	v_fmamk_f32 v166, v156, 0xbc800000, v72
	v_fmamk_f32 v168, v156, 0xbc800000, v70
	v_mul_f32_e32 v169, v169, v169
	v_mul_f32_e32 v167, v167, v167
	v_fmac_f32_e32 v169, v168, v168
	v_fmac_f32_e32 v167, v166, v166
	v_add_f32_e32 v166, v169, v167
	v_fmamk_f32 v167, v156, 0xbc800000, v41
	v_fmamk_f32 v169, v156, 0xbc800000, v39
	v_add_f32_e32 v157, v166, v157
	v_fmamk_f32 v166, v156, 0xbc800000, v40
	v_fmamk_f32 v168, v156, 0xbc800000, v38
	v_mul_f32_e32 v169, v169, v169
	v_mul_f32_e32 v167, v167, v167
	v_fmac_f32_e32 v169, v168, v168
	v_fmac_f32_e32 v167, v166, v166
	v_add_f32_e32 v166, v169, v167
	v_add_f32_e32 v157, v166, v157
	ds_bpermute_b32 v166, v154, v157
	s_waitcnt lgkmcnt(0)
	v_add_f32_e32 v157, v157, v166
	ds_bpermute_b32 v166, v155, v157
	s_and_saveexec_b64 s[6:7], vcc
	s_cbranch_execz .LBB0_335
	s_lshl_b32 s8, s52, 11
	s_add_i32 s8, s2, s8
	v_mul_f32_e32 v156, 0x3c800000, v156
	v_lshl_add_u32 v167, v0, 5, s8
	s_waitcnt lgkmcnt(0)
	v_add_f32_e32 v157, v157, v166
	ds_write_b64 v167, v[156:157]
